# speedup vs baseline: 1.0112x; 1.0038x over previous
; template <int EPI, bool SWP> ...
;     ...
;   f32x4 acc[2][2][4][2];
; #pragma unroll
;   for (int a = 0; a < 2; ++a)
; #pragma unroll
;     for (int b = 0; b < 2; ++b)
; #pragma unroll
;       for (int m = 0; m < 4; ++m)
; #pragma unroll
;         for (int n = 0; n < 2; ++n) acc[a][b][m][n] = f32x4{0.f, 0.f, 0.f, 0.f};
.LBB0_80:
	s_or_b64 exec, exec, s[76:77]
	s_lshl_b32 s69, s17, 8
	s_add_u32 s74, s56, s74
	v_mov_b32_e32 v0, 0
	s_addc_u32 s75, s57, s75
	s_mov_b32 s15, -2
	s_mov_b64 s[76:77], s[72:73]
	v_mov_b32_e32 v1, v0
	v_mov_b64_e32 v[2:3], v[0:1]
	v_mov_b64_e32 v[4:5], v[0:1]
	v_mov_b64_e32 v[6:7], v[0:1]
	v_mov_b64_e32 v[8:9], v[0:1]
	v_mov_b64_e32 v[10:11], v[0:1]
	v_mov_b64_e32 v[12:13], v[0:1]
	v_mov_b64_e32 v[14:15], v[0:1]
	v_mov_b64_e32 v[16:17], v[0:1]
	v_mov_b64_e32 v[18:19], v[0:1]
	v_mov_b64_e32 v[20:21], v[0:1]
	v_mov_b64_e32 v[22:23], v[0:1]
	v_mov_b64_e32 v[24:25], v[0:1]
	v_mov_b64_e32 v[26:27], v[0:1]
	v_mov_b64_e32 v[28:29], v[0:1]
	v_mov_b64_e32 v[30:31], v[0:1]
	v_mov_b64_e32 v[32:33], v[0:1]
	v_mov_b64_e32 v[34:35], v[0:1]
	v_mov_b64_e32 v[36:37], v[0:1]
	v_mov_b64_e32 v[38:39], v[0:1]
	v_mov_b64_e32 v[40:41], v[0:1]
	v_mov_b64_e32 v[42:43], v[0:1]
	v_mov_b64_e32 v[44:45], v[0:1]
	v_mov_b64_e32 v[46:47], v[0:1]
	v_mov_b64_e32 v[48:49], v[0:1]
	v_mov_b64_e32 v[50:51], v[0:1]
	v_mov_b64_e32 v[52:53], v[0:1]
	v_mov_b64_e32 v[54:55], v[0:1]
	v_mov_b64_e32 v[56:57], v[0:1]
	v_mov_b64_e32 v[58:59], v[0:1]
	v_mov_b64_e32 v[60:61], v[0:1]
	v_mov_b64_e32 v[62:63], v[0:1]
	v_mov_b64_e32 v[64:65], v[0:1]
	v_mov_b64_e32 v[66:67], v[0:1]
	v_mov_b64_e32 v[68:69], v[0:1]
	v_mov_b64_e32 v[70:71], v[0:1]
	v_mov_b64_e32 v[72:73], v[0:1]
	v_mov_b64_e32 v[74:75], v[0:1]
	v_mov_b64_e32 v[76:77], v[0:1]
	v_mov_b64_e32 v[78:79], v[0:1]
	v_mov_b64_e32 v[80:81], v[0:1]
	v_mov_b64_e32 v[82:83], v[0:1]
	v_mov_b64_e32 v[84:85], v[0:1]
	v_mov_b64_e32 v[86:87], v[0:1]
	v_mov_b64_e32 v[88:89], v[0:1]
	v_mov_b64_e32 v[90:91], v[0:1]
	v_mov_b64_e32 v[92:93], v[0:1]
	v_mov_b64_e32 v[94:95], v[0:1]
	v_mov_b64_e32 v[96:97], v[0:1]
	v_mov_b64_e32 v[98:99], v[0:1]
	v_mov_b64_e32 v[100:101], v[0:1]
	v_mov_b64_e32 v[102:103], v[0:1]
	v_mov_b64_e32 v[104:105], v[0:1]
	v_mov_b64_e32 v[106:107], v[0:1]
	v_mov_b64_e32 v[108:109], v[0:1]
	v_mov_b64_e32 v[110:111], v[0:1]
	v_mov_b64_e32 v[112:113], v[0:1]
	v_mov_b64_e32 v[114:115], v[0:1]
	v_mov_b64_e32 v[116:117], v[0:1]
	v_mov_b64_e32 v[118:119], v[0:1]
	v_mov_b64_e32 v[120:121], v[0:1]
	v_mov_b64_e32 v[122:123], v[0:1]
	v_mov_b64_e32 v[124:125], v[0:1]
	v_mov_b64_e32 v[126:127], v[0:1]

; template <int EPI, bool SWP> ...
;     ...
;   f32x4 acc[2][2][4][2];
; #pragma unroll
;   for (int a = 0; a < 2; ++a)
; #pragma unroll
;     for (int b = 0; b < 2; ++b)
; #pragma unroll
;       for (int m = 0; m < 4; ++m)
; #pragma unroll
;         for (int n = 0; n < 2; ++n) acc[a][b][m][n] = f32x4{0.f, 0.f, 0.f, 0.f};
.LBB0_122:
	s_ashr_i32 s67, s1, 31
	s_add_u32 s10, s56, s70
	s_addc_u32 s11, s57, s71
	s_add_u32 s58, s56, s68
	v_mov_b32_e32 v0, 0
	s_addc_u32 s59, s57, s69
	s_mov_b32 s68, -2
	s_waitcnt lgkmcnt(0)
	v_mov_b32_e32 v1, v0
	v_mov_b64_e32 v[2:3], v[0:1]
	v_mov_b64_e32 v[4:5], v[0:1]
	v_mov_b64_e32 v[6:7], v[0:1]
	v_mov_b64_e32 v[8:9], v[0:1]
	v_mov_b64_e32 v[10:11], v[0:1]
	v_mov_b64_e32 v[12:13], v[0:1]
	v_mov_b64_e32 v[14:15], v[0:1]
	v_mov_b64_e32 v[16:17], v[0:1]
	v_mov_b64_e32 v[18:19], v[0:1]
	v_mov_b64_e32 v[20:21], v[0:1]
	v_mov_b64_e32 v[22:23], v[0:1]
	v_mov_b64_e32 v[24:25], v[0:1]
	v_mov_b64_e32 v[26:27], v[0:1]
	v_mov_b64_e32 v[28:29], v[0:1]
	v_mov_b64_e32 v[30:31], v[0:1]
	v_mov_b64_e32 v[32:33], v[0:1]
	v_mov_b64_e32 v[34:35], v[0:1]
	v_mov_b64_e32 v[36:37], v[0:1]
	v_mov_b64_e32 v[38:39], v[0:1]
	v_mov_b64_e32 v[40:41], v[0:1]
	v_mov_b64_e32 v[42:43], v[0:1]
	v_mov_b64_e32 v[44:45], v[0:1]
	v_mov_b64_e32 v[46:47], v[0:1]
	v_mov_b64_e32 v[48:49], v[0:1]
	v_mov_b64_e32 v[50:51], v[0:1]
	v_mov_b64_e32 v[52:53], v[0:1]
	v_mov_b64_e32 v[54:55], v[0:1]
	v_mov_b64_e32 v[56:57], v[0:1]
	v_mov_b64_e32 v[58:59], v[0:1]
	v_mov_b64_e32 v[60:61], v[0:1]
	v_mov_b64_e32 v[62:63], v[0:1]
	v_mov_b64_e32 v[64:65], v[0:1]
	v_mov_b64_e32 v[66:67], v[0:1]
	v_mov_b64_e32 v[68:69], v[0:1]
	v_mov_b64_e32 v[70:71], v[0:1]
	v_mov_b64_e32 v[72:73], v[0:1]
	v_mov_b64_e32 v[74:75], v[0:1]
	v_mov_b64_e32 v[76:77], v[0:1]
	v_mov_b64_e32 v[78:79], v[0:1]
	v_mov_b64_e32 v[80:81], v[0:1]
	v_mov_b64_e32 v[82:83], v[0:1]
	v_mov_b64_e32 v[84:85], v[0:1]
	v_mov_b64_e32 v[86:87], v[0:1]
	v_mov_b64_e32 v[88:89], v[0:1]
	v_mov_b64_e32 v[90:91], v[0:1]
	v_mov_b64_e32 v[92:93], v[0:1]
	v_mov_b64_e32 v[94:95], v[0:1]
	v_mov_b64_e32 v[96:97], v[0:1]
	v_mov_b64_e32 v[98:99], v[0:1]
	v_mov_b64_e32 v[100:101], v[0:1]
	v_mov_b64_e32 v[102:103], v[0:1]
	v_mov_b64_e32 v[104:105], v[0:1]
	v_mov_b64_e32 v[106:107], v[0:1]
	v_mov_b64_e32 v[108:109], v[0:1]
	v_mov_b64_e32 v[110:111], v[0:1]
	v_mov_b64_e32 v[112:113], v[0:1]
	v_mov_b64_e32 v[114:115], v[0:1]
	v_mov_b64_e32 v[116:117], v[0:1]
	v_mov_b64_e32 v[118:119], v[0:1]
	v_mov_b64_e32 v[120:121], v[0:1]
	v_mov_b64_e32 v[122:123], v[0:1]
	v_mov_b64_e32 v[124:125], v[0:1]
	v_mov_b64_e32 v[126:127], v[0:1]

; template <int EPI, bool SWP> ...
;     ...
;   f32x4 acc[2][2][4][2];
; #pragma unroll
;   for (int a = 0; a < 2; ++a)
; #pragma unroll
;     for (int b = 0; b < 2; ++b)
; #pragma unroll
;       for (int m = 0; m < 4; ++m)
; #pragma unroll
;         for (int n = 0; n < 2; ++n) acc[a][b][m][n] = f32x4{0.f, 0.f, 0.f, 0.f};
.LBB0_196:
	s_or_b64 exec, exec, s[6:7]
	s_add_u32 s6, s56, s78
	v_mov_b32_e32 v0, 0
	s_addc_u32 s7, s57, s79
	s_mov_b32 s9, -2
	s_mov_b64 s[12:13], s[76:77]
	v_mov_b32_e32 v1, v0
	v_mov_b64_e32 v[2:3], v[0:1]
	v_mov_b64_e32 v[4:5], v[0:1]
	v_mov_b64_e32 v[6:7], v[0:1]
	v_mov_b64_e32 v[8:9], v[0:1]
	v_mov_b64_e32 v[10:11], v[0:1]
	v_mov_b64_e32 v[12:13], v[0:1]
	v_mov_b64_e32 v[14:15], v[0:1]
	v_mov_b64_e32 v[16:17], v[0:1]
	v_mov_b64_e32 v[18:19], v[0:1]
	v_mov_b64_e32 v[20:21], v[0:1]
	v_mov_b64_e32 v[22:23], v[0:1]
	v_mov_b64_e32 v[24:25], v[0:1]
	v_mov_b64_e32 v[26:27], v[0:1]
	v_mov_b64_e32 v[28:29], v[0:1]
	v_mov_b64_e32 v[30:31], v[0:1]
	v_mov_b64_e32 v[32:33], v[0:1]
	v_mov_b64_e32 v[34:35], v[0:1]
	v_mov_b64_e32 v[36:37], v[0:1]
	v_mov_b64_e32 v[38:39], v[0:1]
	v_mov_b64_e32 v[40:41], v[0:1]
	v_mov_b64_e32 v[42:43], v[0:1]
	v_mov_b64_e32 v[44:45], v[0:1]
	v_mov_b64_e32 v[46:47], v[0:1]
	v_mov_b64_e32 v[48:49], v[0:1]
	v_mov_b64_e32 v[50:51], v[0:1]
	v_mov_b64_e32 v[52:53], v[0:1]
	v_mov_b64_e32 v[54:55], v[0:1]
	v_mov_b64_e32 v[56:57], v[0:1]
	v_mov_b64_e32 v[58:59], v[0:1]
	v_mov_b64_e32 v[60:61], v[0:1]
	v_mov_b64_e32 v[62:63], v[0:1]
	v_mov_b64_e32 v[64:65], v[0:1]
	v_mov_b64_e32 v[66:67], v[0:1]
	v_mov_b64_e32 v[68:69], v[0:1]
	v_mov_b64_e32 v[70:71], v[0:1]
	v_mov_b64_e32 v[72:73], v[0:1]
	v_mov_b64_e32 v[74:75], v[0:1]
	v_mov_b64_e32 v[76:77], v[0:1]
	v_mov_b64_e32 v[78:79], v[0:1]
	v_mov_b64_e32 v[80:81], v[0:1]
	v_mov_b64_e32 v[82:83], v[0:1]
	v_mov_b64_e32 v[84:85], v[0:1]
	v_mov_b64_e32 v[86:87], v[0:1]
	v_mov_b64_e32 v[88:89], v[0:1]
	v_mov_b64_e32 v[90:91], v[0:1]
	v_mov_b64_e32 v[92:93], v[0:1]
	v_mov_b64_e32 v[94:95], v[0:1]
	v_mov_b64_e32 v[96:97], v[0:1]
	v_mov_b64_e32 v[98:99], v[0:1]
	v_mov_b64_e32 v[100:101], v[0:1]
	v_mov_b64_e32 v[102:103], v[0:1]
	v_mov_b64_e32 v[104:105], v[0:1]
	v_mov_b64_e32 v[106:107], v[0:1]
	v_mov_b64_e32 v[108:109], v[0:1]
	v_mov_b64_e32 v[110:111], v[0:1]
	v_mov_b64_e32 v[112:113], v[0:1]
	v_mov_b64_e32 v[114:115], v[0:1]
	v_mov_b64_e32 v[116:117], v[0:1]
	v_mov_b64_e32 v[118:119], v[0:1]
	v_mov_b64_e32 v[120:121], v[0:1]
	v_mov_b64_e32 v[122:123], v[0:1]
	v_mov_b64_e32 v[124:125], v[0:1]
	v_mov_b64_e32 v[126:127], v[0:1]

; template <int EPI, bool SWP> ...
;     ...
;   f32x4 acc[2][2][4][2];
; #pragma unroll
;   for (int a = 0; a < 2; ++a)
; #pragma unroll
;     for (int b = 0; b < 2; ++b)
; #pragma unroll
;       for (int m = 0; m < 4; ++m)
; #pragma unroll
;         for (int n = 0; n < 2; ++n) acc[a][b][m][n] = f32x4{0.f, 0.f, 0.f, 0.f};
.LBB0_268:
	s_or_b64 exec, exec, s[6:7]
	s_add_u32 s6, s56, s78
	v_mov_b32_e32 v0, 0
	s_addc_u32 s7, s57, s79
	s_mov_b32 s8, -2
	s_mov_b64 s[10:11], s[76:77]
	v_mov_b32_e32 v1, v0
	v_mov_b64_e32 v[2:3], v[0:1]
	v_mov_b64_e32 v[4:5], v[0:1]
	v_mov_b64_e32 v[6:7], v[0:1]
	v_mov_b64_e32 v[8:9], v[0:1]
	v_mov_b64_e32 v[10:11], v[0:1]
	v_mov_b64_e32 v[12:13], v[0:1]
	v_mov_b64_e32 v[14:15], v[0:1]
	v_mov_b64_e32 v[16:17], v[0:1]
	v_mov_b64_e32 v[18:19], v[0:1]
	v_mov_b64_e32 v[20:21], v[0:1]
	v_mov_b64_e32 v[22:23], v[0:1]
	v_mov_b64_e32 v[24:25], v[0:1]
	v_mov_b64_e32 v[26:27], v[0:1]
	v_mov_b64_e32 v[28:29], v[0:1]
	v_mov_b64_e32 v[30:31], v[0:1]
	v_mov_b64_e32 v[32:33], v[0:1]
	v_mov_b64_e32 v[34:35], v[0:1]
	v_mov_b64_e32 v[36:37], v[0:1]
	v_mov_b64_e32 v[38:39], v[0:1]
	v_mov_b64_e32 v[40:41], v[0:1]
	v_mov_b64_e32 v[42:43], v[0:1]
	v_mov_b64_e32 v[44:45], v[0:1]
	v_mov_b64_e32 v[46:47], v[0:1]
	v_mov_b64_e32 v[48:49], v[0:1]
	v_mov_b64_e32 v[50:51], v[0:1]
	v_mov_b64_e32 v[52:53], v[0:1]
	v_mov_b64_e32 v[54:55], v[0:1]
	v_mov_b64_e32 v[56:57], v[0:1]
	v_mov_b64_e32 v[58:59], v[0:1]
	v_mov_b64_e32 v[60:61], v[0:1]
	v_mov_b64_e32 v[62:63], v[0:1]
	v_mov_b64_e32 v[64:65], v[0:1]
	v_mov_b64_e32 v[66:67], v[0:1]
	v_mov_b64_e32 v[68:69], v[0:1]
	v_mov_b64_e32 v[70:71], v[0:1]
	v_mov_b64_e32 v[72:73], v[0:1]
	v_mov_b64_e32 v[74:75], v[0:1]
	v_mov_b64_e32 v[76:77], v[0:1]
	v_mov_b64_e32 v[78:79], v[0:1]
	v_mov_b64_e32 v[80:81], v[0:1]
	v_mov_b64_e32 v[82:83], v[0:1]
	v_mov_b64_e32 v[84:85], v[0:1]
	v_mov_b64_e32 v[86:87], v[0:1]
	v_mov_b64_e32 v[88:89], v[0:1]
	v_mov_b64_e32 v[90:91], v[0:1]
	v_mov_b64_e32 v[92:93], v[0:1]
	v_mov_b64_e32 v[94:95], v[0:1]
	v_mov_b64_e32 v[96:97], v[0:1]
	v_mov_b64_e32 v[98:99], v[0:1]
	v_mov_b64_e32 v[100:101], v[0:1]
	v_mov_b64_e32 v[102:103], v[0:1]
	v_mov_b64_e32 v[104:105], v[0:1]
	v_mov_b64_e32 v[106:107], v[0:1]
	v_mov_b64_e32 v[108:109], v[0:1]
	v_mov_b64_e32 v[110:111], v[0:1]
	v_mov_b64_e32 v[112:113], v[0:1]
	v_mov_b64_e32 v[114:115], v[0:1]
	v_mov_b64_e32 v[116:117], v[0:1]
	v_mov_b64_e32 v[118:119], v[0:1]
	v_mov_b64_e32 v[120:121], v[0:1]
	v_mov_b64_e32 v[122:123], v[0:1]
	v_mov_b64_e32 v[124:125], v[0:1]
	v_mov_b64_e32 v[126:127], v[0:1]

; #define WAIT_V(n) asm volatile("s_waitcnt vmcnt(%0)" ::"n"(n) : "memory")
; __device__ __forceinline__ void attn_phase(char* shm, const Params& p, const u16* __restrict__ qb, const u16* __restrict__ kb,
;                                            const u16* __restrict__ vT, u16* __restrict__ attn) {
;     ...
;     const u16* vTb = vT + (size_t)tok0 * 1024 + (size_t)h * 128 * S;
;     const u16* kbb = kb + (size_t)tok0 * 1024 + h * 128;
;     const int qpos = qblk * 256 + wid * 32 + l31;
;     const float sl2 = exp2f(-(float)(h + 1)) * LOG2E;
;     __syncthreads();
;     {
;       const u16* qp = qb + (size_t)(tok0 + qpos) * 1024 + h * 128 + hh * 8;
; #pragma unroll
;       for (int c = 0; c < 2; ++c)
; #pragma unroll
;         for (int ks = 0; ks < 4; ++ks)
;           *(bf16x8*)(shm + 65536 + wid * 8192 + (c * 4 + ks) * 1024 + lane * 16) = *(const bf16x8*)(qp + c * 64 + ks * 16);
;     }
;     const unsigned qaddr = (unsigned)(uintptr_t)shm + 65536 + wid * 8192 + lane * 16;
;     f32x16 O[2][4];
; #pragma unroll
;     for (int c = 0; c < 2; ++c)
; #pragma unroll
;       for (int t = 0; t < 4; ++t)
; #pragma unroll
;         for (int i = 0; i < 16; ++i) O[c][t][i] = 0.f;
;     float lsum[2] = {0.f, 0.f};
;     const int wv = __builtin_amdgcn_readfirstlane(wid);
;     const unsigned ksrc0 = (unsigned)(((wv * 4 + (lane >> 4)) * 1024 + (((lane & 15) ^ ((wv * 4 + (lane >> 4)) & 15)) * 8)) * 2);
;     const int vdv0 = wv * 8 + (lane >> 3);
;     const unsigned vsrc0 = (unsigned)((vdv0 * S + (((lane & 7) ^ ((vdv0 >> 1) & 7)) * 8)) * 2);
;     const char* kg = (const char*)kbb; const char* vg = (const char*)vTb;
;     ...
;     const int kx = l31 & 15, vy = (l31 >> 1) & 7;
;     const unsigned lds0 = (unsigned)(uintptr_t)shm;
;     const int kL0 = l31 * 256 + ((kx ^ hh) << 4);
;     const int vM0 = l31 * 128 + ((vy ^ hh) << 4);
;     const int nkt = S >> 6;
;     __syncthreads();
;     A_STAGE(0, 0);
;     WAIT_V(0); __syncthreads();
.LBB0_298:
	s_lshr_b32 s37, s19, 3
	s_ashr_i32 s41, s40, 31
	s_and_b32 s42, s36, s37
	s_lshl_b64 s[36:37], s[40:41], 11
	s_add_u32 s41, s59, s36
	s_addc_u32 s43, s60, s37
	s_lshl_b32 s45, s44, 7
	v_lshl_add_u32 v36, s42, 8, v184
	s_mul_hi_u32 s39, s45, s0
	s_mul_i32 s38, s45, s0
	v_add_u32_e32 v34, s40, v36
	s_lshl_b64 s[38:39], s[38:39], 1
	v_ashrrev_i32_e32 v35, 31, v34
	s_add_u32 s38, s41, s38
	v_lshlrev_b64 v[0:1], 11, v[34:35]
	s_addc_u32 s39, s43, s39
	v_lshl_add_u64 v[0:1], s[46:47], 0, v[0:1]
	s_lshl_b32 s42, s0, 8
	s_mov_b32 s43, s1
	v_lshl_add_u64 v[0:1], v[0:1], 0, s[42:43]
	v_lshl_add_u64 v[0:1], v[0:1], 0, v[166:167]
	s_barrier
	global_load_dwordx4 v[2:5], v[0:1], off
	global_load_dwordx4 v[6:9], v[0:1], off offset:32
	global_load_dwordx4 v[10:13], v[0:1], off offset:64
	global_load_dwordx4 v[14:17], v[0:1], off offset:96
	global_load_dwordx4 v[18:21], v[0:1], off offset:128
	global_load_dwordx4 v[22:25], v[0:1], off offset:160
	global_load_dwordx4 v[26:29], v[0:1], off offset:192
	global_load_dwordx4 v[30:33], v[0:1], off offset:224
	v_readfirstlane_b32 s50, v182
	v_lshlrev_b64 v[168:169], 10, v[34:35]
	s_add_i32 s43, s0, 1
	v_lshl_or_b32 v1, s50, 3, v187
	v_mul_lo_u32 v37, v1, s44
	v_lshrrev_b32_e32 v1, 1, v1
	v_xor_b32_e32 v38, v1, v163
	v_lshlrev_b32_e32 v38, 3, v38
	v_and_or_b32 v34, v38, 56, v37
	v_lshlrev_b32_e32 v38, 1, v34
	s_lshl_b32 s40, s0, 7
	v_cvt_f32_u32_e32 v34, s43
	s_add_u32 s43, s8, s36
	s_addc_u32 s49, s9, s37
	s_add_u32 s48, s43, s42
	s_addc_u32 s49, s49, 0
	v_cmp_lt_f32_e32 vcc, s17, v34
	s_and_b64 s[42:43], vcc, exec
	s_cselect_b32 s51, 0xffffffc0, 0
	v_cndmask_b32_e32 v35, 0, v202, vcc
	v_sub_f32_e32 v34, v35, v34
	s_lshl_b32 s58, s50, 2
	v_exp_f32_e32 v34, v34
	v_bitop3_b32 v39, s58, v163, v186 bitop3:0x36
	v_lshlrev_b32_e32 v39, 4, v39
	v_or_b32_e32 v35, s58, v186
	v_and_b32_e32 v39, 0xf0, v39
	s_lshl_b32 s43, s50, 10
	v_lshl_or_b32 v160, v35, 11, v39
	v_ldexp_f32 v40, v34, s51
	v_lshl_add_u64 v[34:35], s[48:49], 0, v[160:161]
	s_mov_b32 m0, s43
	v_lshl_add_u64 v[34:35], v[34:35], 0, s[4:5]
	s_lshr_b32 s42, s44, 6
	v_bitop3_b32 v1, v1, 7, v163 bitop3:0x48
	v_lshlrev_b32_e32 v1, 4, v1
	v_mov_b32_e32 v0, 0
	v_mul_f32_e32 v170, 0xbfb8aa3b, v40
	s_mov_b32 s41, 0
	v_sub_u32_e32 v205, v162, v36
	v_mov_b32_e32 v171, v170
	v_mov_b32_e32 v178, v170
	v_mov_b32_e32 v179, v170
	v_mov_b32_e32 v64, v0
	v_mov_b32_e32 v65, v0
	v_mov_b32_e32 v66, v0
	v_mov_b32_e32 v67, v0
	v_mov_b32_e32 v68, v0
	v_mov_b32_e32 v69, v0
	v_mov_b32_e32 v70, v0
	v_mov_b32_e32 v71, v0
	v_mov_b32_e32 v72, v0
	v_mov_b32_e32 v73, v0
	v_mov_b32_e32 v74, v0
	v_mov_b32_e32 v75, v0
	v_mov_b32_e32 v76, v0
	v_mov_b32_e32 v77, v0
	v_mov_b32_e32 v78, v0
	v_mov_b32_e32 v79, v0
	v_mov_b32_e32 v96, v0
	v_mov_b32_e32 v97, v0
	v_mov_b32_e32 v98, v0
	v_mov_b32_e32 v99, v0
	v_mov_b32_e32 v100, v0
	v_mov_b32_e32 v101, v0
	s_waitcnt vmcnt(7)
	ds_write_b128 v201, v[2:5]
	s_waitcnt vmcnt(6)
	ds_write_b128 v201, v[6:9] offset:1024
	s_waitcnt vmcnt(5)
	ds_write_b128 v201, v[10:13] offset:2048
	s_waitcnt vmcnt(4)
	ds_write_b128 v201, v[14:17] offset:3072
	s_waitcnt vmcnt(3)
	ds_write_b128 v201, v[18:21] offset:4096
	s_waitcnt vmcnt(2)
	ds_write_b128 v201, v[22:25] offset:5120
	s_waitcnt vmcnt(1)
	ds_write_b128 v201, v[26:29] offset:6144
	s_waitcnt vmcnt(0)
	ds_write_b128 v201, v[30:33] offset:7168
	s_waitcnt lgkmcnt(0)
	s_barrier
	global_load_lds_dwordx4 v160, s[48:49]
	s_add_i32 m0, s43, 0x2000
	v_lshl_add_u32 v160, v37, 1, v1
	global_load_lds_dwordx4 v[34:35], off
	s_add_i32 m0, s43, 0x4000
	v_lshl_or_b32 v1, s50, 13, v200
	global_load_lds_dwordx4 v38, s[38:39]
	s_add_u32 s38, s38, s45
	s_addc_u32 s39, s39, 0
	s_add_i32 m0, s43, 0x6000
	v_mov_b32_e32 v2, v0
	global_load_lds_dwordx4 v38, s[38:39]
	s_mul_hi_u32 s39, s44, s0
	s_mul_i32 s38, s44, s0
	s_lshl_b64 s[38:39], s[38:39], 8
	s_add_u32 s38, s3, s38
	s_addc_u32 s39, s16, s39
	v_lshl_add_u64 v[172:173], s[38:39], 0, v[160:161]
	s_lshl_b64 s[38:39], s[0:1], 8
	s_or_b32 s0, s38, 0x80
	s_mul_i32 s45, s39, s44
	s_mul_hi_u32 s48, s0, s44
	s_add_i32 s48, s48, s45
	s_mul_i32 s0, s0, s44
	s_add_u32 s44, s3, s0
	s_addc_u32 s45, s16, s48
	s_waitcnt vmcnt(0)
	s_add_u32 s38, s56, s38
	v_lshl_add_u64 v[174:175], s[44:45], 0, v[160:161]
	v_add_u32_e32 v160, v1, v39
	s_addc_u32 s39, s57, s39
	v_lshl_add_u64 v[176:177], s[38:39], 0, v[160:161]
	v_mov_b32_e32 v1, v0
	v_mov_b32_e32 v3, v0
	v_mov_b64_e32 v[4:5], v[0:1]
	v_mov_b64_e32 v[6:7], v[0:1]
	v_mov_b64_e32 v[8:9], v[0:1]
	v_mov_b64_e32 v[10:11], v[0:1]
	v_mov_b64_e32 v[12:13], v[0:1]
	v_mov_b64_e32 v[14:15], v[0:1]
	v_mov_b64_e32 v[16:17], v[0:1]
	v_mov_b64_e32 v[18:19], v[0:1]
	v_mov_b64_e32 v[20:21], v[0:1]
	v_mov_b64_e32 v[22:23], v[0:1]
	v_mov_b64_e32 v[24:25], v[0:1]
	v_mov_b64_e32 v[26:27], v[0:1]
	v_mov_b64_e32 v[28:29], v[0:1]
	v_mov_b64_e32 v[30:31], v[0:1]
	v_mov_b64_e32 v[102:103], v[0:1]
	v_mov_b64_e32 v[104:105], v[0:1]
	v_mov_b64_e32 v[106:107], v[0:1]
	v_mov_b64_e32 v[108:109], v[0:1]
	v_mov_b64_e32 v[110:111], v[0:1]
	v_mov_b64_e32 v[32:33], v[0:1]
	v_mov_b64_e32 v[34:35], v[0:1]
	v_mov_b64_e32 v[36:37], v[0:1]
	v_mov_b64_e32 v[38:39], v[0:1]
	v_mov_b64_e32 v[40:41], v[0:1]
	v_mov_b64_e32 v[42:43], v[0:1]
	v_mov_b64_e32 v[44:45], v[0:1]
	v_mov_b64_e32 v[46:47], v[0:1]
	v_mov_b64_e32 v[48:49], v[0:1]
	v_mov_b64_e32 v[50:51], v[0:1]
	v_mov_b64_e32 v[52:53], v[0:1]
	v_mov_b64_e32 v[54:55], v[0:1]
	v_mov_b64_e32 v[56:57], v[0:1]
	v_mov_b64_e32 v[58:59], v[0:1]
	v_mov_b64_e32 v[60:61], v[0:1]
	v_mov_b64_e32 v[62:63], v[0:1]
	v_mov_b64_e32 v[80:81], v[0:1]
	v_mov_b64_e32 v[82:83], v[0:1]
	v_mov_b64_e32 v[84:85], v[0:1]
	v_mov_b64_e32 v[86:87], v[0:1]
	v_mov_b64_e32 v[88:89], v[0:1]
	v_mov_b64_e32 v[90:91], v[0:1]
	v_mov_b64_e32 v[92:93], v[0:1]
	v_mov_b64_e32 v[94:95], v[0:1]
	v_mov_b64_e32 v[112:113], v[0:1]
	v_mov_b64_e32 v[114:115], v[0:1]
	v_mov_b64_e32 v[116:117], v[0:1]
	v_mov_b64_e32 v[118:119], v[0:1]
	v_mov_b64_e32 v[120:121], v[0:1]
	v_mov_b64_e32 v[122:123], v[0:1]
	v_mov_b64_e32 v[124:125], v[0:1]
	v_mov_b64_e32 v[126:127], v[0:1]
	v_mov_b64_e32 v[180:181], v[0:1]
	s_waitcnt vmcnt(0) lgkmcnt(0)
	s_barrier
	s_branch .LBB0_300

; template <int EPI, bool SWP> ...
;     ...
;   f32x4 acc[2][2][4][2];
; #pragma unroll
;   for (int a = 0; a < 2; ++a)
; #pragma unroll
;     for (int b = 0; b < 2; ++b)
; #pragma unroll
;       for (int m = 0; m < 4; ++m)
; #pragma unroll
;         for (int n = 0; n < 2; ++n) acc[a][b][m][n] = f32x4{0.f, 0.f, 0.f, 0.f};
.LBB0_353:
	s_add_u32 s50, s56, s50
	v_mov_b32_e32 v0, 0
	s_addc_u32 s51, s57, s51
	s_mov_b32 s35, -2
	v_mov_b32_e32 v1, v0
	v_mov_b64_e32 v[2:3], v[0:1]
	v_mov_b64_e32 v[4:5], v[0:1]
	v_mov_b64_e32 v[6:7], v[0:1]
	v_mov_b64_e32 v[8:9], v[0:1]
	v_mov_b64_e32 v[10:11], v[0:1]
	v_mov_b64_e32 v[12:13], v[0:1]
	v_mov_b64_e32 v[14:15], v[0:1]
	v_mov_b64_e32 v[16:17], v[0:1]
	v_mov_b64_e32 v[18:19], v[0:1]
	v_mov_b64_e32 v[20:21], v[0:1]
	v_mov_b64_e32 v[22:23], v[0:1]
	v_mov_b64_e32 v[24:25], v[0:1]
	v_mov_b64_e32 v[26:27], v[0:1]
	v_mov_b64_e32 v[28:29], v[0:1]
	v_mov_b64_e32 v[30:31], v[0:1]
	v_mov_b64_e32 v[32:33], v[0:1]
	v_mov_b64_e32 v[34:35], v[0:1]
	v_mov_b64_e32 v[36:37], v[0:1]
	v_mov_b64_e32 v[38:39], v[0:1]
	v_mov_b64_e32 v[40:41], v[0:1]
	v_mov_b64_e32 v[42:43], v[0:1]
	v_mov_b64_e32 v[44:45], v[0:1]
	v_mov_b64_e32 v[46:47], v[0:1]
	v_mov_b64_e32 v[48:49], v[0:1]
	v_mov_b64_e32 v[50:51], v[0:1]
	v_mov_b64_e32 v[52:53], v[0:1]
	v_mov_b64_e32 v[54:55], v[0:1]
	v_mov_b64_e32 v[56:57], v[0:1]
	v_mov_b64_e32 v[58:59], v[0:1]
	v_mov_b64_e32 v[60:61], v[0:1]
	v_mov_b64_e32 v[62:63], v[0:1]
	v_mov_b64_e32 v[64:65], v[0:1]
	v_mov_b64_e32 v[66:67], v[0:1]
	v_mov_b64_e32 v[68:69], v[0:1]
	v_mov_b64_e32 v[70:71], v[0:1]
	v_mov_b64_e32 v[72:73], v[0:1]
	v_mov_b64_e32 v[74:75], v[0:1]
	v_mov_b64_e32 v[76:77], v[0:1]
	v_mov_b64_e32 v[78:79], v[0:1]
	v_mov_b64_e32 v[80:81], v[0:1]
	v_mov_b64_e32 v[82:83], v[0:1]
	v_mov_b64_e32 v[84:85], v[0:1]
	v_mov_b64_e32 v[86:87], v[0:1]
	v_mov_b64_e32 v[88:89], v[0:1]
	v_mov_b64_e32 v[90:91], v[0:1]
	v_mov_b64_e32 v[92:93], v[0:1]
	v_mov_b64_e32 v[94:95], v[0:1]
	v_mov_b64_e32 v[96:97], v[0:1]
	v_mov_b64_e32 v[98:99], v[0:1]
	v_mov_b64_e32 v[100:101], v[0:1]
	v_mov_b64_e32 v[102:103], v[0:1]
	v_mov_b64_e32 v[104:105], v[0:1]
	v_mov_b64_e32 v[106:107], v[0:1]
	v_mov_b64_e32 v[108:109], v[0:1]
	v_mov_b64_e32 v[110:111], v[0:1]
	v_mov_b64_e32 v[112:113], v[0:1]
	v_mov_b64_e32 v[114:115], v[0:1]
	v_mov_b64_e32 v[116:117], v[0:1]
	v_mov_b64_e32 v[118:119], v[0:1]
	v_mov_b64_e32 v[120:121], v[0:1]
	v_mov_b64_e32 v[122:123], v[0:1]
	v_mov_b64_e32 v[124:125], v[0:1]
	v_mov_b64_e32 v[126:127], v[0:1]

; template <int EPI, bool SWP> ...
;     ...
;   f32x4 acc[2][2][4][2];
; #pragma unroll
;   for (int a = 0; a < 2; ++a)
; #pragma unroll
;     for (int b = 0; b < 2; ++b)
; #pragma unroll
;       for (int m = 0; m < 4; ++m)
; #pragma unroll
;         for (int n = 0; n < 2; ++n) acc[a][b][m][n] = f32x4{0.f, 0.f, 0.f, 0.f};
.LBB0_384:
	s_add_u32 s48, s56, s48
	s_addc_u32 s49, s57, s49
	s_add_u32 s50, s56, s50
	v_mov_b32_e32 v0, 0
	s_addc_u32 s51, s57, s51
	s_mov_b32 s35, -2
	v_mov_b32_e32 v1, v0
	v_mov_b64_e32 v[2:3], v[0:1]
	v_mov_b64_e32 v[4:5], v[0:1]
	v_mov_b64_e32 v[6:7], v[0:1]
	v_mov_b64_e32 v[8:9], v[0:1]
	v_mov_b64_e32 v[10:11], v[0:1]
	v_mov_b64_e32 v[12:13], v[0:1]
	v_mov_b64_e32 v[14:15], v[0:1]
	v_mov_b64_e32 v[16:17], v[0:1]
	v_mov_b64_e32 v[18:19], v[0:1]
	v_mov_b64_e32 v[20:21], v[0:1]
	v_mov_b64_e32 v[22:23], v[0:1]
	v_mov_b64_e32 v[24:25], v[0:1]
	v_mov_b64_e32 v[26:27], v[0:1]
	v_mov_b64_e32 v[28:29], v[0:1]
	v_mov_b64_e32 v[30:31], v[0:1]
	v_mov_b64_e32 v[32:33], v[0:1]
	v_mov_b64_e32 v[34:35], v[0:1]
	v_mov_b64_e32 v[36:37], v[0:1]
	v_mov_b64_e32 v[38:39], v[0:1]
	v_mov_b64_e32 v[40:41], v[0:1]
	v_mov_b64_e32 v[42:43], v[0:1]
	v_mov_b64_e32 v[44:45], v[0:1]
	v_mov_b64_e32 v[46:47], v[0:1]
	v_mov_b64_e32 v[48:49], v[0:1]
	v_mov_b64_e32 v[50:51], v[0:1]
	v_mov_b64_e32 v[52:53], v[0:1]
	v_mov_b64_e32 v[54:55], v[0:1]
	v_mov_b64_e32 v[56:57], v[0:1]
	v_mov_b64_e32 v[58:59], v[0:1]
	v_mov_b64_e32 v[60:61], v[0:1]
	v_mov_b64_e32 v[62:63], v[0:1]
	v_mov_b64_e32 v[64:65], v[0:1]
	v_mov_b64_e32 v[66:67], v[0:1]
	v_mov_b64_e32 v[68:69], v[0:1]
	v_mov_b64_e32 v[70:71], v[0:1]
	v_mov_b64_e32 v[72:73], v[0:1]
	v_mov_b64_e32 v[74:75], v[0:1]
	v_mov_b64_e32 v[76:77], v[0:1]
	v_mov_b64_e32 v[78:79], v[0:1]
	v_mov_b64_e32 v[80:81], v[0:1]
	v_mov_b64_e32 v[82:83], v[0:1]
	v_mov_b64_e32 v[84:85], v[0:1]
	v_mov_b64_e32 v[86:87], v[0:1]
	v_mov_b64_e32 v[88:89], v[0:1]
	v_mov_b64_e32 v[90:91], v[0:1]
	v_mov_b64_e32 v[92:93], v[0:1]
	v_mov_b64_e32 v[94:95], v[0:1]
	v_mov_b64_e32 v[96:97], v[0:1]
	v_mov_b64_e32 v[98:99], v[0:1]
	v_mov_b64_e32 v[100:101], v[0:1]
	v_mov_b64_e32 v[102:103], v[0:1]
	v_mov_b64_e32 v[104:105], v[0:1]
	v_mov_b64_e32 v[106:107], v[0:1]
	v_mov_b64_e32 v[108:109], v[0:1]
	v_mov_b64_e32 v[110:111], v[0:1]
	v_mov_b64_e32 v[112:113], v[0:1]
	v_mov_b64_e32 v[114:115], v[0:1]
	v_mov_b64_e32 v[116:117], v[0:1]
	v_mov_b64_e32 v[118:119], v[0:1]
	v_mov_b64_e32 v[120:121], v[0:1]
	v_mov_b64_e32 v[122:123], v[0:1]
	v_mov_b64_e32 v[124:125], v[0:1]
	v_mov_b64_e32 v[126:127], v[0:1]

; template <int EPI, bool SWP> ...
;     ...
;   f32x4 acc[2][2][4][2];
; #pragma unroll
;   for (int a = 0; a < 2; ++a)
; #pragma unroll
;     for (int b = 0; b < 2; ++b)
; #pragma unroll
;       for (int m = 0; m < 4; ++m)
; #pragma unroll
;         for (int n = 0; n < 2; ++n) acc[a][b][m][n] = f32x4{0.f, 0.f, 0.f, 0.f};
.LBB0_427:
	s_add_u32 s70, s56, s70
	v_mov_b32_e32 v0, 0
	s_addc_u32 s71, s57, s71
	s_mov_b32 s61, -2
	s_waitcnt lgkmcnt(0)
	v_mov_b32_e32 v1, v0
	v_mov_b64_e32 v[2:3], v[0:1]
	v_mov_b64_e32 v[4:5], v[0:1]
	v_mov_b64_e32 v[6:7], v[0:1]
	v_mov_b64_e32 v[8:9], v[0:1]
	v_mov_b64_e32 v[10:11], v[0:1]
	v_mov_b64_e32 v[12:13], v[0:1]
	v_mov_b64_e32 v[14:15], v[0:1]
	v_mov_b64_e32 v[16:17], v[0:1]
	v_mov_b64_e32 v[18:19], v[0:1]
	v_mov_b64_e32 v[20:21], v[0:1]
	v_mov_b64_e32 v[22:23], v[0:1]
	v_mov_b64_e32 v[24:25], v[0:1]
	v_mov_b64_e32 v[26:27], v[0:1]
	v_mov_b64_e32 v[28:29], v[0:1]
	v_mov_b64_e32 v[30:31], v[0:1]
	v_mov_b64_e32 v[32:33], v[0:1]
	v_mov_b64_e32 v[34:35], v[0:1]
	v_mov_b64_e32 v[36:37], v[0:1]
	v_mov_b64_e32 v[38:39], v[0:1]
	v_mov_b64_e32 v[40:41], v[0:1]
	v_mov_b64_e32 v[42:43], v[0:1]
	v_mov_b64_e32 v[44:45], v[0:1]
	v_mov_b64_e32 v[46:47], v[0:1]
	v_mov_b64_e32 v[48:49], v[0:1]
	v_mov_b64_e32 v[50:51], v[0:1]
	v_mov_b64_e32 v[52:53], v[0:1]
	v_mov_b64_e32 v[54:55], v[0:1]
	v_mov_b64_e32 v[56:57], v[0:1]
	v_mov_b64_e32 v[58:59], v[0:1]
	v_mov_b64_e32 v[60:61], v[0:1]
	v_mov_b64_e32 v[62:63], v[0:1]
	v_mov_b64_e32 v[64:65], v[0:1]
	v_mov_b64_e32 v[66:67], v[0:1]
	v_mov_b64_e32 v[68:69], v[0:1]
	v_mov_b64_e32 v[70:71], v[0:1]
	v_mov_b64_e32 v[72:73], v[0:1]
	v_mov_b64_e32 v[74:75], v[0:1]
	v_mov_b64_e32 v[76:77], v[0:1]
	v_mov_b64_e32 v[78:79], v[0:1]
	v_mov_b64_e32 v[80:81], v[0:1]
	v_mov_b64_e32 v[82:83], v[0:1]
	v_mov_b64_e32 v[84:85], v[0:1]
	v_mov_b64_e32 v[86:87], v[0:1]
	v_mov_b64_e32 v[88:89], v[0:1]
	v_mov_b64_e32 v[90:91], v[0:1]
	v_mov_b64_e32 v[92:93], v[0:1]
	v_mov_b64_e32 v[94:95], v[0:1]
	v_mov_b64_e32 v[96:97], v[0:1]
	v_mov_b64_e32 v[98:99], v[0:1]
	v_mov_b64_e32 v[100:101], v[0:1]
	v_mov_b64_e32 v[102:103], v[0:1]
	v_mov_b64_e32 v[104:105], v[0:1]
	v_mov_b64_e32 v[106:107], v[0:1]
	v_mov_b64_e32 v[108:109], v[0:1]
	v_mov_b64_e32 v[110:111], v[0:1]
	v_mov_b64_e32 v[112:113], v[0:1]
	v_mov_b64_e32 v[114:115], v[0:1]
	v_mov_b64_e32 v[116:117], v[0:1]
	v_mov_b64_e32 v[118:119], v[0:1]
	v_mov_b64_e32 v[120:121], v[0:1]
	v_mov_b64_e32 v[122:123], v[0:1]
	v_mov_b64_e32 v[124:125], v[0:1]
	v_mov_b64_e32 v[126:127], v[0:1]

; template <int EPI, bool SWP> ...
;     ...
;   f32x4 acc[2][2][4][2];
; #pragma unroll
;   for (int a = 0; a < 2; ++a)
; #pragma unroll
;     for (int b = 0; b < 2; ++b)
; #pragma unroll
;       for (int m = 0; m < 4; ++m)
; #pragma unroll
;         for (int n = 0; n < 2; ++n) acc[a][b][m][n] = f32x4{0.f, 0.f, 0.f, 0.f};
.LBB0_666:
	s_or_b64 exec, exec, s[70:71]
	s_lshl_b32 s61, s73, 8
	s_add_u32 s66, s56, s66
	s_addc_u32 s67, s57, s67
	s_add_u32 s68, s54, s68
	v_mov_b32_e32 v0, 0
	s_addc_u32 s69, s55, s69
	s_mov_b32 s1, -2
	v_mov_b32_e32 v1, v0
	v_mov_b64_e32 v[2:3], v[0:1]
	v_mov_b64_e32 v[4:5], v[0:1]
	v_mov_b64_e32 v[6:7], v[0:1]
	v_mov_b64_e32 v[8:9], v[0:1]
	v_mov_b64_e32 v[10:11], v[0:1]
	v_mov_b64_e32 v[12:13], v[0:1]
	v_mov_b64_e32 v[14:15], v[0:1]
	v_mov_b64_e32 v[16:17], v[0:1]
	v_mov_b64_e32 v[18:19], v[0:1]
	v_mov_b64_e32 v[20:21], v[0:1]
	v_mov_b64_e32 v[22:23], v[0:1]
	v_mov_b64_e32 v[24:25], v[0:1]
	v_mov_b64_e32 v[26:27], v[0:1]
	v_mov_b64_e32 v[28:29], v[0:1]
	v_mov_b64_e32 v[30:31], v[0:1]
	v_mov_b64_e32 v[32:33], v[0:1]
	v_mov_b64_e32 v[34:35], v[0:1]
	v_mov_b64_e32 v[36:37], v[0:1]
	v_mov_b64_e32 v[38:39], v[0:1]
	v_mov_b64_e32 v[40:41], v[0:1]
	v_mov_b64_e32 v[42:43], v[0:1]
	v_mov_b64_e32 v[44:45], v[0:1]
	v_mov_b64_e32 v[46:47], v[0:1]
	v_mov_b64_e32 v[48:49], v[0:1]
	v_mov_b64_e32 v[50:51], v[0:1]
	v_mov_b64_e32 v[52:53], v[0:1]
	v_mov_b64_e32 v[54:55], v[0:1]
	v_mov_b64_e32 v[56:57], v[0:1]
	v_mov_b64_e32 v[58:59], v[0:1]
	v_mov_b64_e32 v[60:61], v[0:1]
	v_mov_b64_e32 v[62:63], v[0:1]
	v_mov_b64_e32 v[64:65], v[0:1]
	v_mov_b64_e32 v[66:67], v[0:1]
	v_mov_b64_e32 v[68:69], v[0:1]
	v_mov_b64_e32 v[70:71], v[0:1]
	v_mov_b64_e32 v[72:73], v[0:1]
	v_mov_b64_e32 v[74:75], v[0:1]
	v_mov_b64_e32 v[76:77], v[0:1]
	v_mov_b64_e32 v[78:79], v[0:1]
	v_mov_b64_e32 v[80:81], v[0:1]
	v_mov_b64_e32 v[82:83], v[0:1]
	v_mov_b64_e32 v[84:85], v[0:1]
	v_mov_b64_e32 v[86:87], v[0:1]
	v_mov_b64_e32 v[88:89], v[0:1]
	v_mov_b64_e32 v[90:91], v[0:1]
	v_mov_b64_e32 v[92:93], v[0:1]
	v_mov_b64_e32 v[94:95], v[0:1]
	v_mov_b64_e32 v[96:97], v[0:1]
	v_mov_b64_e32 v[98:99], v[0:1]
	v_mov_b64_e32 v[100:101], v[0:1]
	v_mov_b64_e32 v[102:103], v[0:1]
	v_mov_b64_e32 v[104:105], v[0:1]
	v_mov_b64_e32 v[106:107], v[0:1]
	v_mov_b64_e32 v[108:109], v[0:1]
	v_mov_b64_e32 v[110:111], v[0:1]
	v_mov_b64_e32 v[112:113], v[0:1]
	v_mov_b64_e32 v[114:115], v[0:1]
	v_mov_b64_e32 v[116:117], v[0:1]
	v_mov_b64_e32 v[118:119], v[0:1]
	v_mov_b64_e32 v[120:121], v[0:1]
	v_mov_b64_e32 v[122:123], v[0:1]
	v_mov_b64_e32 v[124:125], v[0:1]
	v_mov_b64_e32 v[126:127], v[0:1]

; template <int EPI, bool SWP> ...
;     ...
;   f32x4 acc[2][2][4][2];
; #pragma unroll
;   for (int a = 0; a < 2; ++a)
; #pragma unroll
;     for (int b = 0; b < 2; ++b)
; #pragma unroll
;       for (int m = 0; m < 4; ++m)
; #pragma unroll
;         for (int n = 0; n < 2; ++n) acc[a][b][m][n] = f32x4{0.f, 0.f, 0.f, 0.f};
.LBB0_708:
	s_add_u32 s70, s56, s91
	v_mov_b32_e32 v0, 0
	s_addc_u32 s71, s57, s92
	s_mov_b32 s91, -2
	s_waitcnt lgkmcnt(0)
	v_mov_b32_e32 v1, v0
	v_mov_b64_e32 v[2:3], v[0:1]
	v_mov_b64_e32 v[4:5], v[0:1]
	v_mov_b64_e32 v[6:7], v[0:1]
	v_mov_b64_e32 v[8:9], v[0:1]
	v_mov_b64_e32 v[10:11], v[0:1]
	v_mov_b64_e32 v[12:13], v[0:1]
	v_mov_b64_e32 v[14:15], v[0:1]
	v_mov_b64_e32 v[16:17], v[0:1]
	v_mov_b64_e32 v[18:19], v[0:1]
	v_mov_b64_e32 v[20:21], v[0:1]
	v_mov_b64_e32 v[22:23], v[0:1]
	v_mov_b64_e32 v[24:25], v[0:1]
	v_mov_b64_e32 v[26:27], v[0:1]
	v_mov_b64_e32 v[28:29], v[0:1]
	v_mov_b64_e32 v[30:31], v[0:1]
	v_mov_b64_e32 v[32:33], v[0:1]
	v_mov_b64_e32 v[34:35], v[0:1]
	v_mov_b64_e32 v[36:37], v[0:1]
	v_mov_b64_e32 v[38:39], v[0:1]
	v_mov_b64_e32 v[40:41], v[0:1]
	v_mov_b64_e32 v[42:43], v[0:1]
	v_mov_b64_e32 v[44:45], v[0:1]
	v_mov_b64_e32 v[46:47], v[0:1]
	v_mov_b64_e32 v[48:49], v[0:1]
	v_mov_b64_e32 v[50:51], v[0:1]
	v_mov_b64_e32 v[52:53], v[0:1]
	v_mov_b64_e32 v[54:55], v[0:1]
	v_mov_b64_e32 v[56:57], v[0:1]
	v_mov_b64_e32 v[58:59], v[0:1]
	v_mov_b64_e32 v[60:61], v[0:1]
	v_mov_b64_e32 v[62:63], v[0:1]
	v_mov_b64_e32 v[64:65], v[0:1]
	v_mov_b64_e32 v[66:67], v[0:1]
	v_mov_b64_e32 v[68:69], v[0:1]
	v_mov_b64_e32 v[70:71], v[0:1]
	v_mov_b64_e32 v[72:73], v[0:1]
	v_mov_b64_e32 v[74:75], v[0:1]
	v_mov_b64_e32 v[76:77], v[0:1]
	v_mov_b64_e32 v[78:79], v[0:1]
	v_mov_b64_e32 v[80:81], v[0:1]
	v_mov_b64_e32 v[82:83], v[0:1]
	v_mov_b64_e32 v[84:85], v[0:1]
	v_mov_b64_e32 v[86:87], v[0:1]
	v_mov_b64_e32 v[88:89], v[0:1]
	v_mov_b64_e32 v[90:91], v[0:1]
	v_mov_b64_e32 v[92:93], v[0:1]
	v_mov_b64_e32 v[94:95], v[0:1]
	v_mov_b64_e32 v[96:97], v[0:1]
	v_mov_b64_e32 v[98:99], v[0:1]
	v_mov_b64_e32 v[100:101], v[0:1]
	v_mov_b64_e32 v[102:103], v[0:1]
	v_mov_b64_e32 v[104:105], v[0:1]
	v_mov_b64_e32 v[106:107], v[0:1]
	v_mov_b64_e32 v[108:109], v[0:1]
	v_mov_b64_e32 v[110:111], v[0:1]
	v_mov_b64_e32 v[112:113], v[0:1]
	v_mov_b64_e32 v[114:115], v[0:1]
	v_mov_b64_e32 v[116:117], v[0:1]
	v_mov_b64_e32 v[118:119], v[0:1]
	v_mov_b64_e32 v[120:121], v[0:1]
	v_mov_b64_e32 v[122:123], v[0:1]
	v_mov_b64_e32 v[124:125], v[0:1]
	v_mov_b64_e32 v[126:127], v[0:1]
